# diff-attention QK fragment reads pipelined one step ahead (second register set, counted lgkmcnt) + static priority raise for waves 4-7 in the two attention phases; on top of conv+gelu epilogue trim, p
# speedup vs baseline: 1.0092x; 1.0092x over previous
; __global__ void __launch_bounds__(NTHREADS, 2) mk_fwd(Args args) {
;     ...
;     if (IN(2)) {
;         constexpr int NB_UNITS = 512, NA_UNITS = 1536;
;         const int wslot2 = vcu & 7; int ucnt2 = 0;
.LBB0_208:
	v_readlane_b32 s2, v254, 1
	s_cmpk_lt_u32 s2, 0x100
	s_cbranch_scc1 .Lprio_skip_p2
	s_setprio 1

; #define LAS __attribute__((address_space(3)))
; template <bool QL>
; __device__ __forceinline__ void qkt(f32x16& p0, f32x16& p1, const char* Ks, const bf16x8* qr, const LAS char* qlds, int r32, int hi) {
;     p0 = f32x16{}; p1 = f32x16{};
; #pragma unroll
;     for (int d0 = 0; d0 < 8; ++d0) { int cb = (d0 * 16 + hi * 8) * 2;
;         bf16x8 b0 = *reinterpret_cast<const bf16x8*>(Ks + KSWZ(r32, cb));
;         bf16x8 b1 = *reinterpret_cast<const bf16x8*>(Ks + KSWZ(32 + r32, cb));
;         bf16x8 q;
;         if constexpr (QL) { if (d0 < 4) q = qr[d0]; else q = *(const volatile LAS bf16x8*)(qlds + (d0 - 4) * 1024); } else q = qr[d0];
;         p0 = __builtin_amdgcn_mfma_f32_32x32x16_bf16(b0, q, p0, 0, 0, 0);
;         p1 = __builtin_amdgcn_mfma_f32_32x32x16_bf16(b1, q, p1, 0, 0, 0); }
; }
; template <int MODE> __device__ __forceinline__ float apply_mode(f32x16& p0, f32x16& p1, int t, const ModeCtx& c, const LAS float* lut, int hi) {
;     ...
;         const int klo = t * 64;
;         if (klo - (c.qlo + 31) >= c.far_thr) cb = c.cpos;
;         else if (c.qlo - (klo + 63) >= c.far_thr) cb = c.cneg;
;         else {
;         const LAS float* L = lut + (c.lidx + t * 64);
; #pragma unroll
;         for (int g = 0; g < 4; ++g) {
;             float b0[4], b1[4];
; #pragma unroll
;             for (int q = 0; q < 4; ++q) { b0[q] = L[8 * g + q]; b1[q] = L[32 + 8 * g + q]; }
; #pragma unroll
;             for (int q = 0; q < 4; ++q) { p0[4 * g + q] += b0[q]; p1[4 * g + q] += b1[q]; }
;         }
.LBB0_227:
	s_and_b32 s2, s51, 1
	s_lshl_b32 s3, s2, 14
	s_xor_b32 s26, s3, 0x4000
	s_add_i32 s26, s59, s26
	v_lshl_add_u64 v[128:129], s[52:53], 0, v[216:217]
	s_mov_b32 m0, s26
	s_nop 0
	global_load_lds_dwordx4 v[128:129], off
	s_add_i32 m0, s26, 0x2000
	s_lshl_b32 s26, s2, 15
	v_lshl_add_u64 v[128:129], s[52:53], 0, v[214:215]
	s_xor_b32 s2, s26, 0x8000
	global_load_lds_dwordx4 v[128:129], off
	s_add_i32 s2, s58, s2
	v_lshl_add_u64 v[128:129], s[52:53], 0, v[212:213]
	v_lshl_add_u64 v[130:131], v[128:129], 0, s[44:45]
	s_mov_b32 m0, s2
	v_lshl_add_u64 v[128:129], v[128:129], 0, s[46:47]
	global_load_lds_dwordx4 v[130:131], off
	v_lshl_add_u64 v[130:131], s[52:53], 0, v[202:203]
	v_lshl_add_u64 v[132:133], v[130:131], 0, s[44:45]
	s_add_i32 m0, s2, 0x2000
	s_nop 0
	global_load_lds_dwordx4 v[132:133], off
	s_add_i32 m0, s2, 0x4000
	s_nop 0
	global_load_lds_dwordx4 v[128:129], off
	v_lshl_add_u64 v[128:129], v[130:131], 0, s[46:47]
	s_add_i32 m0, s2, 0x6000
	s_nop 0
	global_load_lds_dwordx4 v[128:129], off
	s_add_i32 s2, s3, 0
	s_add_i32 s2, s2, 0x10000
	v_add3_u32 v132, s2, v236, v228
	ds_read_b128 v[128:131], v132
	ds_read_b128 v[132:135], v132 offset:8192
	v_add3_u32 v190, s2, v235, v228
	ds_read_b128 v[186:189], v190
	ds_read_b128 v[190:193], v190 offset:8192
	v_add3_u32 v244, s2, v234, v228
	ds_read_b128 v[240:243], v244
	ds_read_b128 v[244:247], v244 offset:8192
	s_cmpk_gt_i32 s94, 0x24d
	s_waitcnt lgkmcnt(4)
	v_mfma_f32_32x32x16_bf16 v[144:159], v[128:131], v[182:185], 0
	v_mfma_f32_32x32x16_bf16 v[128:143], v[132:135], v[182:185], 0
	s_waitcnt lgkmcnt(2)
	v_mfma_f32_32x32x16_bf16 v[144:159], v[186:189], v[178:181], v[144:159]
	v_mfma_f32_32x32x16_bf16 v[128:143], v[190:193], v[178:181], v[128:143]
	v_add3_u32 v190, s2, v233, v228
	ds_read_b128 v[186:189], v190
	ds_read_b128 v[190:193], v190 offset:8192
	s_waitcnt lgkmcnt(2)
	v_mfma_f32_32x32x16_bf16 v[144:159], v[240:243], v[174:177], v[144:159]
	v_mfma_f32_32x32x16_bf16 v[128:143], v[244:247], v[174:177], v[128:143]
	v_add3_u32 v244, s2, v232, v228
	ds_read_b128 v[240:243], v244
	ds_read_b128 v[244:247], v244 offset:8192
	ds_read_b128 v[248:251], v227
	s_waitcnt lgkmcnt(3)
	v_mfma_f32_32x32x16_bf16 v[144:159], v[186:189], v[170:173], v[144:159]
	v_mfma_f32_32x32x16_bf16 v[128:143], v[190:193], v[170:173], v[128:143]
	v_add3_u32 v190, s2, v231, v228
	ds_read_b128 v[186:189], v190
	ds_read_b128 v[190:193], v190 offset:8192
	ds_read_b128 v[194:197], v227 offset:1024
	s_waitcnt lgkmcnt(3)
	v_mfma_f32_32x32x16_bf16 v[144:159], v[240:243], v[248:251], v[144:159]
	v_mfma_f32_32x32x16_bf16 v[128:143], v[244:247], v[248:251], v[128:143]
	v_add3_u32 v244, s2, v230, v228
	ds_read_b128 v[240:243], v244
	ds_read_b128 v[244:247], v244 offset:8192
	ds_read_b128 v[248:251], v227 offset:2048
	s_waitcnt lgkmcnt(3)
	v_mfma_f32_32x32x16_bf16 v[144:159], v[186:189], v[194:197], v[144:159]
	v_mfma_f32_32x32x16_bf16 v[128:143], v[190:193], v[194:197], v[128:143]
	v_add3_u32 v190, s2, v229, v228
	ds_read_b128 v[186:189], v190
	ds_read_b128 v[190:193], v190 offset:8192
	ds_read_b128 v[194:197], v227 offset:3072
	s_waitcnt lgkmcnt(3)
	v_mfma_f32_32x32x16_bf16 v[144:159], v[240:243], v[248:251], v[144:159]
	v_mfma_f32_32x32x16_bf16 v[128:143], v[244:247], v[248:251], v[128:143]
	s_waitcnt lgkmcnt(0)
	v_mfma_f32_32x32x16_bf16 v[144:159], v[186:189], v[194:197], v[144:159]
	v_mfma_f32_32x32x16_bf16 v[128:143], v[190:193], v[194:197], v[128:143]
	s_cbranch_scc1 .LBB0_230
	s_cmpk_gt_i32 s64, 0x22e
	s_cbranch_scc1 .LBB0_231
	v_add_u32_e32 v239, s50, v237
	v_add_u32_e32 v186, 0x25700, v239
	v_add_u32_e32 v188, 0x25780, v239
	v_add_u32_e32 v190, 0x25708, v239
	v_add_u32_e32 v192, 0x25788, v239
	ds_read2_b32 v[186:187], v186 offset1:1
	ds_read2_b32 v[188:189], v188 offset1:1
	ds_read2_b32 v[190:191], v190 offset1:1
	ds_read2_b32 v[192:193], v192 offset1:1
	v_add_u32_e32 v194, 0x25720, v239
	v_add_u32_e32 v196, 0x257a0, v239
	v_add_u32_e32 v198, 0x25728, v239
	v_add_u32_e32 v200, 0x257a8, v239
	v_add_u32_e32 v240, 0x25740, v239
	v_add_u32_e32 v242, 0x257c0, v239
	v_add_u32_e32 v244, 0x25748, v239
	v_add_u32_e32 v246, 0x257c8, v239
	v_add_u32_e32 v248, 0x25760, v239
	v_add_u32_e32 v250, 0x257e0, v239
	v_add_u32_e32 v252, 0x25768, v239
	v_add_u32_e32 v239, 0x257e8, v239
	ds_read2_b32 v[194:195], v194 offset1:1
	ds_read2_b32 v[196:197], v196 offset1:1
	ds_read2_b32 v[198:199], v198 offset1:1
	ds_read2_b32 v[200:201], v200 offset1:1
	ds_read2_b32 v[240:241], v240 offset1:1
	ds_read2_b32 v[242:243], v242 offset1:1
	ds_read2_b32 v[244:245], v244 offset1:1
	ds_read2_b32 v[246:247], v246 offset1:1
	ds_read2_b32 v[248:249], v248 offset1:1
	ds_read2_b32 v[250:251], v250 offset1:1
	ds_read2_b32 v[252:253], v252 offset1:1
	s_waitcnt lgkmcnt(0)
	v_pk_add_f32 v[144:145], v[144:145], v[186:187]
	ds_read2_b32 v[186:187], v239 offset1:1
	v_pk_add_f32 v[156:157], v[156:157], v[248:249]
	v_pk_add_f32 v[154:155], v[154:155], v[244:245]
	v_pk_add_f32 v[158:159], v[158:159], v[252:253]
	v_pk_add_f32 v[152:153], v[152:153], v[240:241]
	v_pk_add_f32 v[150:151], v[150:151], v[198:199]
	v_pk_add_f32 v[148:149], v[148:149], v[194:195]
	v_pk_add_f32 v[146:147], v[146:147], v[190:191]
	s_waitcnt lgkmcnt(0)
	v_pk_add_f32 v[142:143], v[142:143], v[186:187]
	v_pk_add_f32 v[140:141], v[140:141], v[250:251]
	v_pk_add_f32 v[138:139], v[138:139], v[246:247]
	v_pk_add_f32 v[136:137], v[136:137], v[242:243]
	v_pk_add_f32 v[134:135], v[134:135], v[200:201]
	v_pk_add_f32 v[132:133], v[132:133], v[196:197]
	v_pk_add_f32 v[130:131], v[130:131], v[192:193]
	v_pk_add_f32 v[128:129], v[128:129], v[188:189]
	s_mov_b32 s27, 0
	s_branch .LBB0_232

; #define LAS __attribute__((address_space(3)))
; __device__ __forceinline__ void xcd_barrier(unsigned* bar, unsigned x, volatile LAS unsigned* st, unsigned G, int tid) {
;     asm volatile("s_waitcnt vmcnt(0)" ::: "memory");
;     __syncthreads();
;     if (tid == 0) {
;         __builtin_amdgcn_s_waitcnt(0);
;         unsigned nloc = st[0], nx = st[1];
;         if (nloc == 0u) { xcd_barrier_complete(bar, x, G, nloc, nx); st[0] = nloc; st[1] = nx; }
.LBB0_870:
	v_readlane_b32 s0, v254, 11
	v_readlane_b32 s1, v254, 12
	s_cmp_gt_i32 s1, 3
	v_readlane_b32 s2, v254, 27
	s_cselect_b64 s[0:1], -1, 0
	v_readlane_b32 s3, v254, 28
	s_and_b64 s[2:3], s[2:3], s[0:1]
	s_andn2_b64 vcc, exec, s[2:3]
	s_cbranch_vccnz .LBB0_924
	s_waitcnt vmcnt(0)
	v_mov_b32_e32 v0, 0
	s_setprio 0
	s_waitcnt vmcnt(0)
	v_readlane_b32 s2, v254, 1
	v_mbcnt_lo_u32_b32 v0, -1, v0
	v_mbcnt_hi_u32_b32 v0, -1, v0
	s_sub_i32 s2, 0, s2
	v_cmp_eq_u32_e32 vcc, s2, v0
	s_barrier
	s_and_saveexec_b64 s[2:3], vcc
	s_cbranch_execz .LBB0_923
	s_add_i32 s4, 0, 0x23fc0
	v_mov_b32_e32 v0, s4
	s_waitcnt vmcnt(0) expcnt(0) lgkmcnt(0)
	ds_read_b32 v2, v0
	s_add_i32 s4, 0, 0x23fc4
	v_mov_b32_e32 v0, s4
	ds_read_b32 v0, v0
	s_waitcnt lgkmcnt(1)
	v_cmp_ne_u32_e32 vcc, 0, v2
	s_cbranch_vccnz .LBB0_887
	v_readlane_b32 s44, v254, 7
	v_readlane_b32 s46, v254, 9
	v_readlane_b32 s47, v254, 10
	s_add_u32 s4, s46, 0x60200
	s_addc_u32 s5, s47, 0
	s_add_u32 s6, s46, 0x60400
	s_addc_u32 s7, s47, 0
	s_add_u32 s8, s46, 0x60500
	s_addc_u32 s9, s47, 0
	s_add_u32 s10, s46, 0x60600
	s_addc_u32 s11, s47, 0
	s_add_u32 s12, s46, 0x60700
	s_addc_u32 s13, s47, 0
	s_add_u32 s14, s46, 0x60800
	s_addc_u32 s15, s47, 0
	s_add_u32 s16, s46, 0x60900
	s_addc_u32 s17, s47, 0
	s_add_u32 s18, s46, 0x60a00
	s_addc_u32 s19, s47, 0
	s_add_u32 s26, s46, 0x60b00
	s_addc_u32 s27, s47, 0
	s_add_u32 s28, s46, 0x60c00
	s_addc_u32 s29, s47, 0
	s_add_u32 s30, s46, 0x60d00
	s_addc_u32 s31, s47, 0
	s_add_u32 s34, s46, 0x60e00
	s_addc_u32 s35, s47, 0
	s_add_u32 s36, s46, 0x60f00
	s_addc_u32 s37, s47, 0
	s_add_u32 s38, s46, 0x61000
	s_addc_u32 s39, s47, 0
	s_add_u32 s40, s46, 0x61100
	s_addc_u32 s41, s47, 0
	s_add_u32 s42, s46, 0x61200
	s_addc_u32 s43, s47, 0
	v_readlane_b32 s45, v254, 8
	s_add_u32 s44, s46, 0x61300
	s_addc_u32 s45, s47, 0
	s_mov_b32 s22, 1
	v_mov_b32_e32 v16, 0
	s_branch .LBB0_875

; #define LAS __attribute__((address_space(3)))
; __device__ __forceinline__ void xcd_barrier(unsigned* bar, unsigned x, volatile LAS unsigned* st, unsigned G, int tid) {
;     asm volatile("s_waitcnt vmcnt(0)" ::: "memory");
;     __syncthreads();
;     if (tid == 0) {
;         __builtin_amdgcn_s_waitcnt(0);
;         unsigned nloc = st[0], nx = st[1];
;         if (nloc == 0u) { xcd_barrier_complete(bar, x, G, nloc, nx); st[0] = nloc; st[1] = nx; }
.LBB0_1865:
	v_readlane_b32 s0, v254, 11
	v_readlane_b32 s1, v254, 12
	s_cmp_gt_i32 s1, 11
	v_readlane_b32 s2, v254, 46
	s_cselect_b64 s[0:1], -1, 0
	v_readlane_b32 s3, v254, 47
	s_and_b64 s[2:3], s[2:3], s[0:1]
	s_andn2_b64 vcc, exec, s[2:3]
	s_cbranch_vccnz .LBB0_1919
	s_waitcnt vmcnt(0)
	v_mov_b32_e32 v0, 0
	s_setprio 0
	s_waitcnt vmcnt(0)
	v_readlane_b32 s2, v254, 1
	v_mbcnt_lo_u32_b32 v0, -1, v0
	v_mbcnt_hi_u32_b32 v0, -1, v0
	s_sub_i32 s2, 0, s2
	v_cmp_eq_u32_e32 vcc, s2, v0
	s_waitcnt lgkmcnt(0)
	s_barrier
	s_and_saveexec_b64 s[2:3], vcc
	s_cbranch_execz .LBB0_1918
	s_add_i32 s4, 0, 0x23fc0
	v_mov_b32_e32 v0, s4
	s_waitcnt vmcnt(0) expcnt(0) lgkmcnt(0)
	ds_read_b32 v2, v0
	s_add_i32 s4, 0, 0x23fc4
	v_mov_b32_e32 v0, s4
	ds_read_b32 v0, v0
	s_waitcnt lgkmcnt(1)
	v_cmp_ne_u32_e32 vcc, 0, v2
	s_cbranch_vccnz .LBB0_1882
	v_readlane_b32 s36, v254, 7
	v_readlane_b32 s38, v254, 9
	v_readlane_b32 s39, v254, 10
	s_add_u32 s4, s38, 0x60200
	s_addc_u32 s5, s39, 0
	s_add_u32 s6, s38, 0x60400
	s_addc_u32 s7, s39, 0
	s_add_u32 s8, s38, 0x60500
	s_addc_u32 s9, s39, 0
	s_add_u32 s10, s38, 0x60600
	s_addc_u32 s11, s39, 0
	s_add_u32 s12, s38, 0x60700
	s_addc_u32 s13, s39, 0
	s_add_u32 s14, s38, 0x60800
	s_addc_u32 s15, s39, 0
	s_add_u32 s16, s38, 0x60900
	s_addc_u32 s17, s39, 0
	s_add_u32 s18, s38, 0x60a00
	s_addc_u32 s19, s39, 0
	s_add_u32 s20, s38, 0x60b00
	s_addc_u32 s21, s39, 0
	s_add_u32 s22, s38, 0x60c00
	s_addc_u32 s23, s39, 0
	s_add_u32 s24, s38, 0x60d00
	s_addc_u32 s25, s39, 0
	s_add_u32 s26, s38, 0x60e00
	s_addc_u32 s27, s39, 0
	s_add_u32 s28, s38, 0x60f00
	s_addc_u32 s29, s39, 0
	s_add_u32 s30, s38, 0x61000
	s_addc_u32 s31, s39, 0
	s_add_u32 s34, s38, 0x61100
	s_addc_u32 s35, s39, 0
	v_readlane_b32 s37, v254, 8
	s_add_u32 s36, s38, 0x61200
	s_addc_u32 s37, s39, 0
	s_add_u32 s38, s38, 0x61300
	s_addc_u32 s39, s39, 0
	s_mov_b32 s33, 1
	v_mov_b32_e32 v16, 0
	s_branch .LBB0_1870
